# adds PEER LN-finish: permlane/DPP wave sums and batched lng/lnb/scn/shn loads (two batches instead of 16 serialized round trips)
# speedup vs baseline: 1.0045x; 1.0045x over previous
.LBB0_786:
	v_lshrrev_b32_e32 v2, 12, v4
	v_add_u32_e32 v2, 1, v2
	v_cndmask_b32_e64 v4, v2, 0, s[10:11]
	s_add_u32 s10, s36, 0x12684000
	v_lshl_add_u64 v[0:1], s[36:37], 0, v[0:1]
	s_addc_u32 s11, s37, 0
	v_lshl_add_u64 v[62:63], v[0:1], 0, s[96:97]
	v_add_u32_e32 v2, s60, v4
	v_mov_b64_e32 v[0:1], s[10:11]
	v_mad_u64_u32 v[2:3], s[10:11], v2, s41, v[0:1]
	s_mov_b64 s[10:11], 0xa000
	s_nop 0
	v_lshl_add_u64 v[64:65], v[2:3], 0, s[10:11]
	s_add_u32 s12, s36, s24
	v_add_u32_e32 v2, s48, v4
	s_addc_u32 s13, s37, s25
	v_mad_u64_u32 v[40:41], s[36:37], v2, s41, v[0:1]
	v_and_b32_e32 v0, 60, v232
	s_movk_i32 s36, 0xff80
	v_and_or_b32 v54, v224, s36, v0
	v_ashrrev_i32_e32 v55, 31, v54
	v_lshlrev_b64 v[60:61], 2, v[54:55]
	v_lshl_add_u64 v[4:5], v[64:65], 0, v[60:61]
	v_add_u32_e32 v34, 0x400, v54
	v_lshl_add_u64 v[26:27], v[62:63], 0, v[60:61]
	global_load_dwordx4 v[4:7], v[4:5], off
	v_ashrrev_i32_e32 v35, 31, v34
	global_load_dwordx4 v[0:3], v[26:27], off
	v_or_b32_e32 v56, 64, v54
	v_lshlrev_b64 v[50:51], 2, v[34:35]
	v_ashrrev_i32_e32 v57, 31, v56
	v_lshl_add_u64 v[34:35], v[62:63], 0, v[50:51]
	v_lshl_add_u64 v[44:45], v[64:65], 0, v[50:51]
	s_waitcnt lgkmcnt(0)
	v_lshl_add_u64 v[12:13], v[56:57], 2, v[64:65]
	global_load_dwordx4 v[34:37], v[34:35], off
	v_add_u32_e32 v58, 0x200, v54
	global_load_dwordx4 v[74:77], v[44:45], off
	v_add_u32_e32 v44, 0x440, v54
	global_load_dwordx4 v[12:15], v[12:13], off
	v_ashrrev_i32_e32 v45, 31, v44
	global_load_dwordx4 v[8:11], v[26:27], off offset:256
	global_load_dwordx4 v[18:21], v[26:27], off offset:2048
	v_lshlrev_b64 v[48:49], 2, v[44:45]
	v_ashrrev_i32_e32 v59, 31, v58
	v_lshl_add_u64 v[44:45], v[62:63], 0, v[48:49]
	v_lshl_add_u64 v[22:23], v[58:59], 2, v[64:65]
	global_load_dwordx4 v[78:81], v[44:45], off
	v_lshl_add_u64 v[44:45], v[64:65], 0, v[48:49]
	global_load_dwordx4 v[22:25], v[22:23], off
	v_add_u32_e32 v52, 0x240, v54
	global_load_dwordx4 v[70:73], v[44:45], off
	v_add_u32_e32 v44, 0x600, v54
	v_ashrrev_i32_e32 v45, 31, v44
	v_ashrrev_i32_e32 v53, 31, v52
	v_lshlrev_b64 v[46:47], 2, v[44:45]
	v_lshl_add_u64 v[30:31], v[52:53], 2, v[64:65]
	v_lshl_add_u64 v[44:45], v[62:63], 0, v[46:47]
	global_load_dwordx4 v[26:29], v[26:27], off offset:2304
	s_add_u32 s10, s12, 0x1272b180
	global_load_dwordx4 v[30:33], v[30:31], off
	s_addc_u32 s11, s13, 0
	global_load_dwordx4 v[82:85], v[44:45], off
	v_lshl_add_u64 v[44:45], v[64:65], 0, v[46:47]
	global_load_dwordx4 v[66:69], v[44:45], off
	v_add_u32_e32 v44, 0x640, v54
	v_ashrrev_i32_e32 v45, 31, v44
	v_lshlrev_b64 v[44:45], 2, v[44:45]
	v_lshl_add_u64 v[62:63], v[62:63], 0, v[44:45]
	global_load_dwordx4 v[86:89], v[62:63], off
	v_lshl_add_u64 v[62:63], v[64:65], 0, v[44:45]
	global_load_dwordx4 v[62:65], v[62:63], off
	s_add_u32 s12, s12, 0x1273b180
	s_addc_u32 s13, s13, 0
	s_mov_b64 s[0:1], 0x2000
	v_lshl_add_u64 v[42:43], v[40:41], 0, s[0:1]
	s_waitcnt vmcnt(15)
	v_pk_mul_f32 v[4:5], v[118:119], v[4:5]
	v_pk_mul_f32 v[6:7], v[120:121], v[6:7]
	s_waitcnt vmcnt(14)
	v_pk_fma_f32 v[0:1], v[0:1], s[86:87], v[4:5] op_sel_hi:[1,0,1]
	v_pk_fma_f32 v[2:3], v[2:3], s[86:87], v[6:7] op_sel_hi:[1,0,1]
	v_add_f32_e32 v4, 0, v0
	v_add_f32_e32 v4, v1, v4
	v_add_f32_e32 v4, v2, v4
	v_add_f32_e32 v4, v3, v4
	s_waitcnt vmcnt(12)
	v_pk_mul_f32 v[74:75], v[138:139], v[74:75]
	s_nop 0
	v_pk_fma_f32 v[34:35], v[34:35], s[86:87], v[74:75] op_sel_hi:[1,0,1]
	s_waitcnt vmcnt(11)
	v_pk_mul_f32 v[12:13], v[122:123], v[12:13]
	v_pk_mul_f32 v[14:15], v[124:125], v[14:15]
	s_waitcnt vmcnt(10)
	v_pk_fma_f32 v[12:13], v[8:9], s[86:87], v[12:13] op_sel_hi:[1,0,1]
	v_pk_fma_f32 v[14:15], v[10:11], s[86:87], v[14:15] op_sel_hi:[1,0,1]
	v_add_f32_e32 v4, v12, v4
	v_add_f32_e32 v4, v13, v4
	v_add_f32_e32 v4, v14, v4
	v_add_f32_e32 v4, v15, v4
	v_pk_mul_f32 v[76:77], v[140:141], v[76:77]
	s_waitcnt vmcnt(7)
	v_pk_mul_f32 v[22:23], v[126:127], v[22:23]
	s_nop 0
	v_pk_fma_f32 v[18:19], v[18:19], s[86:87], v[22:23] op_sel_hi:[1,0,1]
	v_pk_mul_f32 v[24:25], v[128:129], v[24:25]
	v_add_f32_e32 v4, v18, v4
	v_pk_fma_f32 v[24:25], v[20:21], s[86:87], v[24:25] op_sel_hi:[1,0,1]
	v_add_f32_e32 v4, v19, v4
	v_add_f32_e32 v4, v24, v4
	v_add_f32_e32 v4, v25, v4
	v_pk_fma_f32 v[36:37], v[36:37], s[86:87], v[76:77] op_sel_hi:[1,0,1]
	s_waitcnt vmcnt(6)
	v_pk_mul_f32 v[72:73], v[144:145], v[72:73]
	v_lshl_add_u64 v[20:21], s[10:11], 0, v[60:61]
	s_waitcnt vmcnt(4)
	v_pk_mul_f32 v[30:31], v[134:135], v[30:31]
	v_pk_mul_f32 v[32:33], v[136:137], v[32:33]
	v_pk_fma_f32 v[26:27], v[26:27], s[86:87], v[30:31] op_sel_hi:[1,0,1]
	v_pk_fma_f32 v[28:29], v[28:29], s[86:87], v[32:33] op_sel_hi:[1,0,1]
	v_add_f32_e32 v4, v26, v4
	v_add_f32_e32 v4, v27, v4
	v_add_f32_e32 v4, v28, v4
	v_add_f32_e32 v4, v29, v4
	v_add_f32_e32 v4, v34, v4
	s_waitcnt vmcnt(2)
	v_pk_mul_f32 v[68:69], v[152:153], v[68:69]
	v_add_f32_e32 v4, v35, v4
	s_waitcnt vmcnt(0)
	v_pk_mul_f32 v[64:65], v[132:133], v[64:65]
	v_pk_mul_f32 v[90:91], v[130:131], v[62:63]
	v_pk_fma_f32 v[62:63], v[88:89], s[86:87], v[64:65] op_sel_hi:[1,0,1]
	v_pk_fma_f32 v[64:65], v[86:87], s[86:87], v[90:91] op_sel_hi:[1,0,1]
	v_pk_mul_f32 v[86:87], v[150:151], v[66:67]
	v_pk_fma_f32 v[66:67], v[84:85], s[86:87], v[68:69] op_sel_hi:[1,0,1]
	v_pk_fma_f32 v[68:69], v[82:83], s[86:87], v[86:87] op_sel_hi:[1,0,1]
	v_pk_mul_f32 v[82:83], v[142:143], v[70:71]
	v_add_f32_e32 v4, v36, v4
	v_pk_fma_f32 v[70:71], v[80:81], s[86:87], v[72:73] op_sel_hi:[1,0,1]
	v_pk_fma_f32 v[72:73], v[78:79], s[86:87], v[82:83] op_sel_hi:[1,0,1]
	v_add_f32_e32 v4, v37, v4
	v_add_f32_e32 v4, v72, v4
	v_add_f32_e32 v4, v73, v4
	v_add_f32_e32 v4, v70, v4
	v_add_f32_e32 v4, v71, v4
	v_add_f32_e32 v4, v68, v4
	v_add_f32_e32 v4, v69, v4
	v_add_f32_e32 v4, v66, v4
	v_add_f32_e32 v4, v67, v4
	v_add_f32_e32 v4, v64, v4
	v_add_f32_e32 v4, v65, v4
	v_add_f32_e32 v4, v62, v4
	v_add_f32_e32 v4, v63, v4
	v_lshl_add_u64 v[22:23], s[12:13], 0, v[60:61]
	global_load_dwordx4 v[8:11], v[20:21], off
	global_load_dwordx4 v[84:87], v[22:23], off
	s_waitcnt lgkmcnt(0)
	v_mov_b32_e32 v5, v4
	s_nop 1
	v_permlane32_swap_b32_e32 v5, v4
	v_add_f32_e32 v4, v4, v5
	v_mov_b32_e32 v5, v4
	s_nop 1
	v_permlane16_swap_b32_e32 v5, v4
	v_add_f32_e32 v4, v4, v5
	s_nop 1
	v_add_f32_dpp v4, v4, v4 row_ror:8 row_mask:0xf bank_mask:0xf
	s_nop 1
	v_add_f32_dpp v4, v4, v4 row_ror:4 row_mask:0xf bank_mask:0xf
	s_nop 1
	v_add_f32_dpp v4, v4, v4 row_ror:2 row_mask:0xf bank_mask:0xf
	s_nop 1
	v_add_f32_dpp v4, v4, v4 row_ror:1 row_mask:0xf bank_mask:0xf
	global_load_dwordx4 v[102:105], v[20:21], off offset:256
	global_load_dwordx4 v[166:169], v[22:23], off offset:256
	global_load_dwordx4 v[106:109], v[20:21], off offset:2048
	global_load_dwordx4 v[170:173], v[22:23], off offset:2048
	global_load_dwordx4 v[110:113], v[20:21], off offset:2304
	global_load_dwordx4 v[174:177], v[22:23], off offset:2304
	v_lshl_add_u64 v[182:183], s[10:11], 0, v[50:51]
	v_lshl_add_u64 v[184:185], s[12:13], 0, v[50:51]
	global_load_dwordx4 v[114:117], v[182:183], off
	global_load_dwordx4 v[196:199], v[184:185], off
	v_lshl_add_u64 v[182:183], s[10:11], 0, v[48:49]
	v_lshl_add_u64 v[184:185], s[12:13], 0, v[48:49]
	global_load_dwordx4 v[154:157], v[182:183], off
	global_load_dwordx4 v[200:203], v[184:185], off
	v_lshl_add_u64 v[182:183], s[10:11], 0, v[46:47]
	v_lshl_add_u64 v[184:185], s[12:13], 0, v[46:47]
	global_load_dwordx4 v[158:161], v[182:183], off
	global_load_dwordx4 v[204:207], v[184:185], off
	v_lshl_add_u64 v[182:183], s[10:11], 0, v[44:45]
	v_lshl_add_u64 v[184:185], s[12:13], 0, v[44:45]
	global_load_dwordx4 v[162:165], v[182:183], off
	global_load_dwordx4 v[208:211], v[184:185], off
	v_lshl_add_u64 v[182:183], v[42:43], 0, v[60:61]
	v_lshl_add_u64 v[184:185], v[40:41], 0, v[60:61]
	global_load_dwordx4 v[234:237], v[182:183], off
	global_load_dwordx4 v[246:249], v[184:185], off
	global_load_dwordx4 v[238:241], v[182:183], off offset:256
	global_load_dwordx4 v[250:253], v[184:185], off offset:256
	global_load_dwordx4 v[242:245], v[182:183], off offset:2048
	global_load_dwordx4 v[146:149], v[184:185], off offset:2048
	v_mul_f32_e32 v6, 0x3a000000, v4
	v_pk_add_f32 v[0:1], v[0:1], v[6:7] op_sel_hi:[1,0] neg_lo:[0,1] neg_hi:[0,1]
	v_pk_add_f32 v[2:3], v[2:3], v[6:7] op_sel_hi:[1,0] neg_lo:[0,1] neg_hi:[0,1]
	v_pk_mul_f32 v[88:89], v[0:1], v[0:1]
	v_pk_mul_f32 v[90:91], v[2:3], v[2:3]
	v_add_f32_e32 v17, v88, v89
	v_pk_add_f32 v[80:81], v[12:13], v[6:7] op_sel_hi:[1,0] neg_lo:[0,1] neg_hi:[0,1]
	v_add_f32_e32 v17, v90, v17
	v_pk_mul_f32 v[92:93], v[80:81], v[80:81]
	v_add_f32_e32 v17, v91, v17
	v_pk_add_f32 v[82:83], v[14:15], v[6:7] op_sel_hi:[1,0] neg_lo:[0,1] neg_hi:[0,1]
	v_add_f32_e32 v17, v92, v17
	v_pk_mul_f32 v[94:95], v[82:83], v[82:83]
	v_add_f32_e32 v17, v93, v17
	v_pk_add_f32 v[76:77], v[18:19], v[6:7] op_sel_hi:[1,0] neg_lo:[0,1] neg_hi:[0,1]
	v_add_f32_e32 v17, v94, v17
	v_pk_mul_f32 v[18:19], v[76:77], v[76:77]
	v_add_f32_e32 v17, v95, v17
	v_pk_add_f32 v[78:79], v[24:25], v[6:7] op_sel_hi:[1,0] neg_lo:[0,1] neg_hi:[0,1]
	v_add_f32_e32 v17, v18, v17
	v_pk_mul_f32 v[96:97], v[78:79], v[78:79]
	v_add_f32_e32 v17, v19, v17
	v_pk_add_f32 v[32:33], v[26:27], v[6:7] op_sel_hi:[1,0] neg_lo:[0,1] neg_hi:[0,1]
	v_add_f32_e32 v17, v96, v17
	v_pk_mul_f32 v[98:99], v[32:33], v[32:33]
	v_add_f32_e32 v17, v97, v17
	v_pk_add_f32 v[74:75], v[28:29], v[6:7] op_sel_hi:[1,0] neg_lo:[0,1] neg_hi:[0,1]
	v_add_f32_e32 v17, v98, v17
	v_pk_mul_f32 v[100:101], v[74:75], v[74:75]
	v_add_f32_e32 v17, v99, v17
	v_pk_add_f32 v[30:31], v[34:35], v[6:7] op_sel_hi:[1,0] neg_lo:[0,1] neg_hi:[0,1]
	v_add_f32_e32 v17, v100, v17
	v_pk_mul_f32 v[34:35], v[30:31], v[30:31]
	v_add_f32_e32 v17, v101, v17
	v_pk_add_f32 v[28:29], v[36:37], v[6:7] op_sel_hi:[1,0] neg_lo:[0,1] neg_hi:[0,1]
	v_add_f32_e32 v17, v34, v17
	v_pk_mul_f32 v[36:37], v[28:29], v[28:29]
	v_add_f32_e32 v17, v35, v17
	v_pk_add_f32 v[26:27], v[72:73], v[6:7] op_sel_hi:[1,0] neg_lo:[0,1] neg_hi:[0,1]
	v_add_f32_e32 v17, v36, v17
	v_pk_mul_f32 v[72:73], v[26:27], v[26:27]
	v_add_f32_e32 v17, v37, v17
	v_pk_add_f32 v[24:25], v[70:71], v[6:7] op_sel_hi:[1,0] neg_lo:[0,1] neg_hi:[0,1]
	v_add_f32_e32 v17, v72, v17
	v_pk_mul_f32 v[70:71], v[24:25], v[24:25]
	v_add_f32_e32 v17, v73, v17
	v_pk_add_f32 v[14:15], v[68:69], v[6:7] op_sel_hi:[1,0] neg_lo:[0,1] neg_hi:[0,1]
	v_add_f32_e32 v17, v70, v17
	v_pk_mul_f32 v[68:69], v[14:15], v[14:15]
	v_add_f32_e32 v17, v71, v17
	v_pk_add_f32 v[12:13], v[66:67], v[6:7] op_sel_hi:[1,0] neg_lo:[0,1] neg_hi:[0,1]
	v_add_f32_e32 v17, v68, v17
	v_pk_mul_f32 v[66:67], v[12:13], v[12:13]
	v_add_f32_e32 v17, v69, v17
	v_pk_add_f32 v[4:5], v[64:65], v[6:7] op_sel_hi:[1,0] neg_lo:[0,1] neg_hi:[0,1]
	v_add_f32_e32 v17, v66, v17
	v_pk_mul_f32 v[64:65], v[4:5], v[4:5]
	v_add_f32_e32 v17, v67, v17
	v_pk_add_f32 v[6:7], v[62:63], v[6:7] op_sel_hi:[1,0] neg_lo:[0,1] neg_hi:[0,1]
	v_add_f32_e32 v17, v64, v17
	v_pk_mul_f32 v[62:63], v[6:7], v[6:7]
	v_add_f32_e32 v17, v65, v17
	v_add_f32_e32 v17, v62, v17
	v_add_f32_e32 v17, v63, v17
	s_waitcnt lgkmcnt(0)
	v_mov_b32_e32 v18, v17
	s_nop 1
	v_permlane32_swap_b32_e32 v18, v17
	v_add_f32_e32 v17, v17, v18
	v_mov_b32_e32 v18, v17
	s_nop 1
	v_permlane16_swap_b32_e32 v18, v17
	v_add_f32_e32 v17, v17, v18
	s_nop 1
	v_add_f32_dpp v17, v17, v17 row_ror:8 row_mask:0xf bank_mask:0xf
	s_nop 1
	v_add_f32_dpp v17, v17, v17 row_ror:4 row_mask:0xf bank_mask:0xf
	s_nop 1
	v_add_f32_dpp v17, v17, v17 row_ror:2 row_mask:0xf bank_mask:0xf
	s_nop 1
	v_add_f32_dpp v17, v17, v17 row_ror:1 row_mask:0xf bank_mask:0xf
	v_fmamk_f32 v17, v17, 0x3a000000, v186
	v_cmp_gt_f32_e32 vcc, s54, v17
	v_mul_f32_e32 v18, 0x4b800000, v17
	s_nop 0
	v_cndmask_b32_e32 v17, v17, v18, vcc
	v_rsq_f32_e32 v17, v17
	s_nop 0
	v_mul_f32_e32 v18, 0x45800000, v17
	v_cndmask_b32_e32 v18, v17, v18, vcc
	v_pk_mul_f32 v[0:1], v[0:1], v[18:19] op_sel_hi:[1,0]
	v_pk_mul_f32 v[2:3], v[2:3], v[18:19] op_sel_hi:[1,0]
	v_mov_b32_e32 v19, v18
	s_waitcnt vmcnt(0)
	v_pk_fma_f32 v[0:1], v[8:9], v[0:1], v[84:85]
	v_pk_fma_f32 v[2:3], v[10:11], v[2:3], v[86:87]
	v_lshl_add_u64 v[10:11], v[38:39], 0, v[60:61]
	v_lshl_add_u64 v[8:9], v[54:55], 1, v[178:179]
	global_store_dwordx4 v[10:11], v[0:3], off
	v_pk_mul_f32 v[80:81], v[80:81], v[18:19]
	v_pk_mul_f32 v[82:83], v[82:83], v[18:19]
	v_pk_fma_f32 v[102:103], v[80:81], v[102:103], v[166:167]
	v_pk_fma_f32 v[104:105], v[82:83], v[104:105], v[168:169]
	global_store_dwordx4 v[10:11], v[102:105], off offset:256
	v_pk_mul_f32 v[76:77], v[76:77], v[18:19]
	v_pk_mul_f32 v[78:79], v[78:79], v[18:19]
	v_pk_fma_f32 v[106:107], v[76:77], v[106:107], v[170:171]
	v_pk_fma_f32 v[108:109], v[78:79], v[108:109], v[172:173]
	global_store_dwordx4 v[10:11], v[106:109], off offset:2048
	v_pk_mul_f32 v[32:33], v[32:33], v[18:19]
	v_pk_mul_f32 v[74:75], v[74:75], v[18:19]
	v_pk_fma_f32 v[110:111], v[32:33], v[110:111], v[174:175]
	v_pk_fma_f32 v[112:113], v[74:75], v[112:113], v[176:177]
	global_store_dwordx4 v[10:11], v[110:113], off offset:2304
	v_pk_mul_f32 v[30:31], v[30:31], v[18:19]
	v_pk_mul_f32 v[28:29], v[28:29], v[18:19]
	v_pk_fma_f32 v[114:115], v[30:31], v[114:115], v[196:197]
	v_pk_fma_f32 v[116:117], v[28:29], v[116:117], v[198:199]
	v_lshl_add_u64 v[182:183], v[38:39], 0, v[50:51]
	global_store_dwordx4 v[182:183], v[114:117], off
	v_pk_mul_f32 v[26:27], v[26:27], v[18:19]
	v_pk_mul_f32 v[24:25], v[24:25], v[18:19]
	v_pk_fma_f32 v[154:155], v[26:27], v[154:155], v[200:201]
	v_pk_fma_f32 v[156:157], v[24:25], v[156:157], v[202:203]
	v_lshl_add_u64 v[182:183], v[38:39], 0, v[48:49]
	global_store_dwordx4 v[182:183], v[154:157], off
	v_pk_mul_f32 v[14:15], v[14:15], v[18:19]
	v_pk_mul_f32 v[12:13], v[12:13], v[18:19]
	v_pk_fma_f32 v[158:159], v[14:15], v[158:159], v[204:205]
	v_pk_fma_f32 v[160:161], v[12:13], v[160:161], v[206:207]
	v_lshl_add_u64 v[182:183], v[38:39], 0, v[46:47]
	global_store_dwordx4 v[182:183], v[158:161], off
	v_pk_mul_f32 v[4:5], v[4:5], v[18:19]
	v_pk_mul_f32 v[6:7], v[6:7], v[18:19]
	v_pk_fma_f32 v[162:163], v[4:5], v[162:163], v[208:209]
	v_pk_fma_f32 v[164:165], v[6:7], v[164:165], v[210:211]
	v_lshl_add_u64 v[182:183], v[38:39], 0, v[44:45]
	global_store_dwordx4 v[182:183], v[162:165], off
	s_and_b64 vcc, exec, s[4:5]
	s_cbranch_vccnz .LBB0_731
	v_lshl_add_u64 v[182:183], v[42:43], 0, v[60:61]
	v_lshl_add_u64 v[184:185], v[40:41], 0, v[60:61]
	global_load_dwordx4 v[166:169], v[182:183], off offset:2304
	global_load_dwordx4 v[204:207], v[184:185], off offset:2304
	v_lshl_add_u64 v[182:183], v[42:43], 0, v[50:51]
	v_lshl_add_u64 v[184:185], v[40:41], 0, v[50:51]
	global_load_dwordx4 v[170:173], v[182:183], off
	global_load_dwordx4 v[208:211], v[184:185], off
	v_lshl_add_u64 v[182:183], v[42:43], 0, v[48:49]
	v_lshl_add_u64 v[184:185], v[40:41], 0, v[48:49]
	global_load_dwordx4 v[174:177], v[182:183], off
	global_load_dwordx4 v[28:31], v[184:185], off
	v_lshl_add_u64 v[182:183], v[42:43], 0, v[46:47]
	v_lshl_add_u64 v[184:185], v[40:41], 0, v[46:47]
	global_load_dwordx4 v[196:199], v[182:183], off
	global_load_dwordx4 v[24:27], v[184:185], off
	v_lshl_add_u64 v[182:183], v[42:43], 0, v[44:45]
	v_lshl_add_u64 v[184:185], v[40:41], 0, v[44:45]
	global_load_dwordx4 v[200:203], v[182:183], off
	global_load_dwordx4 v[12:15], v[184:185], off
	v_pk_add_f32 v[234:235], v[234:235], 1.0 op_sel_hi:[1,0]
	v_pk_add_f32 v[236:237], v[236:237], 1.0 op_sel_hi:[1,0]
	v_pk_fma_f32 v[0:1], v[0:1], v[234:235], v[246:247]
	v_pk_fma_f32 v[2:3], v[2:3], v[236:237], v[248:249]
	v_cvt_pk_bf16_f32 v0, v0, v1
	v_cvt_pk_bf16_f32 v1, v2, v3
	global_store_dwordx2 v[8:9], v[0:1], off
	v_pk_add_f32 v[238:239], v[238:239], 1.0 op_sel_hi:[1,0]
	v_pk_add_f32 v[240:241], v[240:241], 1.0 op_sel_hi:[1,0]
	v_pk_fma_f32 v[102:103], v[102:103], v[238:239], v[250:251]
	v_pk_fma_f32 v[104:105], v[104:105], v[240:241], v[252:253]
	v_cvt_pk_bf16_f32 v102, v102, v103
	v_cvt_pk_bf16_f32 v103, v104, v105
	global_store_dwordx2 v[8:9], v[102:103], off offset:128
	v_pk_add_f32 v[242:243], v[242:243], 1.0 op_sel_hi:[1,0]
	v_pk_add_f32 v[244:245], v[244:245], 1.0 op_sel_hi:[1,0]
	v_pk_fma_f32 v[106:107], v[106:107], v[242:243], v[146:147]
	v_pk_fma_f32 v[108:109], v[108:109], v[244:245], v[148:149]
	v_cvt_pk_bf16_f32 v106, v106, v107
	v_cvt_pk_bf16_f32 v107, v108, v109
	global_store_dwordx2 v[8:9], v[106:107], off offset:1024
	s_waitcnt vmcnt(3)
	v_pk_add_f32 v[166:167], v[166:167], 1.0 op_sel_hi:[1,0]
	v_pk_add_f32 v[168:169], v[168:169], 1.0 op_sel_hi:[1,0]
	v_pk_fma_f32 v[110:111], v[110:111], v[166:167], v[204:205]
	v_pk_fma_f32 v[112:113], v[112:113], v[168:169], v[206:207]
	v_cvt_pk_bf16_f32 v110, v110, v111
	v_cvt_pk_bf16_f32 v111, v112, v113
	global_store_dwordx2 v[8:9], v[110:111], off offset:1152
	v_pk_add_f32 v[170:171], v[170:171], 1.0 op_sel_hi:[1,0]
	v_pk_add_f32 v[172:173], v[172:173], 1.0 op_sel_hi:[1,0]
	v_pk_fma_f32 v[114:115], v[114:115], v[170:171], v[208:209]
	v_pk_fma_f32 v[116:117], v[116:117], v[172:173], v[210:211]
	v_cvt_pk_bf16_f32 v114, v114, v115
	v_cvt_pk_bf16_f32 v115, v116, v117
	global_store_dwordx2 v[8:9], v[114:115], off offset:2048
	v_pk_add_f32 v[174:175], v[174:175], 1.0 op_sel_hi:[1,0]
	v_pk_add_f32 v[176:177], v[176:177], 1.0 op_sel_hi:[1,0]
	v_pk_fma_f32 v[154:155], v[154:155], v[174:175], v[28:29]
	v_pk_fma_f32 v[156:157], v[156:157], v[176:177], v[30:31]
	v_cvt_pk_bf16_f32 v154, v154, v155
	v_cvt_pk_bf16_f32 v155, v156, v157
	global_store_dwordx2 v[8:9], v[154:155], off offset:2176
	v_pk_add_f32 v[196:197], v[196:197], 1.0 op_sel_hi:[1,0]
	v_pk_add_f32 v[198:199], v[198:199], 1.0 op_sel_hi:[1,0]
	v_pk_fma_f32 v[158:159], v[158:159], v[196:197], v[24:25]
	v_pk_fma_f32 v[160:161], v[160:161], v[198:199], v[26:27]
	v_cvt_pk_bf16_f32 v158, v158, v159
	v_cvt_pk_bf16_f32 v159, v160, v161
	global_store_dwordx2 v[8:9], v[158:159], off offset:3072
	v_pk_add_f32 v[200:201], v[200:201], 1.0 op_sel_hi:[1,0]
	v_pk_add_f32 v[202:203], v[202:203], 1.0 op_sel_hi:[1,0]
	v_pk_fma_f32 v[162:163], v[162:163], v[200:201], v[12:13]
	v_pk_fma_f32 v[164:165], v[164:165], v[202:203], v[14:15]
	v_cvt_pk_bf16_f32 v162, v162, v163
	v_cvt_pk_bf16_f32 v163, v164, v165
	global_store_dwordx2 v[8:9], v[162:163], off offset:3200
	s_branch .LBB0_731
